# adds: attention fast path for unmasked tiles - QK keys 0-31 first, exps of that half overlap the QK MFMAs of keys 32-63, PV MFMAs overlap the second half exps; masked tiles and the rare rescale keep t
# speedup vs baseline: 1.0165x; 1.0057x over previous
; DI void attn_tile(bool MASK, const LAS unsigned char* Ks, const LAS unsigned char* Vs, const bf16x8 (&qr)[6], f32x16& negm, float& mrun, float& lrun, f32x16& o0, f32x16& o1,
;                                        int kv0, int qrow, int r32, int hi) {
;     ...
;     __builtin_amdgcn_s_setprio(1);
;     {
;         const bf16x8 a0 = *(const LAS bf16x8*)(Ks + r32 * 208 + hi * 16);
;         const bf16x8 a1 = *(const LAS bf16x8*)(Ks + (32 + r32) * 208 + hi * 16);
;         p0 = MFMA32(a0, qr[0], negm); p1 = MFMA32(a1, qr[0], negm);
;     }
; #pragma unroll
;     for (int d0 = 1; d0 < 6; ++d0) {
;         const bf16x8 a0 = *(const LAS bf16x8*)(Ks + r32 * 208 + (2 * d0 + hi) * 16);
;         const bf16x8 a1 = *(const LAS bf16x8*)(Ks + (32 + r32) * 208 + (2 * d0 + hi) * 16);
;         p0 = MFMA32(a0, qr[d0], p0); p1 = MFMA32(a1, qr[d0], p1);
;     }
;     __builtin_amdgcn_s_setprio(0);
;     if (MASK) {
;         asm volatile("" ::: "memory");
; #pragma unroll
;         for (int r = 0; r < 16; ++r) { const int kv = kv0 + crow(r, hi); if (kv > qrow) p0[r] = -INFINITY; if (kv + 32 > qrow) p1[r] = -INFINITY; }
;     }
;     float mxa = max3f(p0[0], p0[1], p1[0]), mxb = max3f(p0[2], p0[3], p1[1]); mxa = max3f(mxa, p1[2], p1[3]);
; #pragma unroll
;     for (int r = 4; r < 16; r += 4) { mxa = max3f(mxa, p0[r], p0[r + 1]); mxb = max3f(mxb, p0[r + 2], p0[r + 3]); mxa = max3f(mxa, p1[r], p1[r + 1]); mxb = max3f(mxb, p1[r + 2], p1[r + 3]); }
;     float mx = max2f(mxa, mxb);
;     mx = max2f(mx, __shfl_xor(mx, 32));
;     if (__any(mx > AT_THR)) {
;         const float dm = max2f(mx, 0.f);
;         const float alpha = __builtin_amdgcn_exp2f(-dm);
;         mrun += dm; lrun *= alpha;
; #pragma unroll
;         for (int r = 0; r < 16; ++r) { o0[r] *= alpha; o1[r] *= alpha; p0[r] -= dm; p1[r] -= dm; negm[r] = -mrun; }
;     }
;     float ls = 0.f;
; #pragma unroll
;     for (int r = 0; r < 16; ++r) { p0[r] = __builtin_amdgcn_exp2f(p0[r]); p1[r] = __builtin_amdgcn_exp2f(p1[r]); ls += p0[r] + p1[r]; }
;     lrun += ls;
; #pragma unroll
;     for (int ks = 0; ks < 4; ++ks) {
;         u32x4 pp;
;         if (ks == 0) { pp.x = pk2(p0[0], p0[1]); pp.y = pk2(p0[2], p0[3]); pp.z = pk2(p0[4], p0[5]); pp.w = pk2(p0[6], p0[7]); }
;         else if (ks == 1) { pp.x = pk2(p0[8], p0[9]); pp.y = pk2(p0[10], p0[11]); pp.z = pk2(p0[12], p0[13]); pp.w = pk2(p0[14], p0[15]); }
.LBB0_849:
	s_add_i32 s33, s23, 4
	s_min_i32 s33, s33, s20
	v_mad_i64_i32 v[4:5], s[34:35], s33, v161, v[190:191]
	v_mad_i64_i32 v[6:7], s[34:35], s33, v161, v[194:195]
	v_add3_u32 v0, v204, v199, s29
	s_lshl_b32 s34, s33, 6
	s_waitcnt lgkmcnt(0)
	s_barrier
	s_waitcnt vmcnt(3)
	ds_write_b128 v209, v[130:133] offset:22016
	ds_write_b128 v210, v[106:109] offset:22016
	ds_write2_b64 v0, v[110:111], v[112:113] offset1:1
	s_ashr_i32 s35, s34, 31
	global_load_dwordx4 v[130:133], v[4:5], off
	global_load_dwordx4 v[106:109], v[6:7], off
	v_lshl_add_u64 v[4:5], s[34:35], 1, v[192:193]
	global_load_dwordx4 v[110:113], v[4:5], off
	s_cmp_gt_i32 s21, s22
	s_cbranch_scc1 .LBB0_855
	s_cmp_lt_i32 s23, s12
	s_setprio 1
	v_add_u32_e32 v0, v206, v160
	ds_read_b128 v[4:7], v0
	ds_read_b128 v[8:11], v0 offset:32
	ds_read_b128 v[12:15], v0 offset:64
	ds_read_b128 v[214:217], v0 offset:96
	ds_read_b128 v[218:221], v0 offset:128
	ds_read_b128 v[222:225], v0 offset:160
	ds_read_b128 v[226:229], v0 offset:6656
	ds_read_b128 v[230:233], v0 offset:6688
	s_waitcnt lgkmcnt(7)
	v_mfma_f32_32x32x16_bf16 v[82:97], v[4:7], v[154:157], v[50:65]
	ds_read_b128 v[234:237], v0 offset:6720
	s_waitcnt lgkmcnt(7)
	v_mfma_f32_32x32x16_bf16 v[82:97], v[8:11], v[150:153], v[82:97]
	ds_read_b128 v[238:241], v0 offset:6752
	s_waitcnt lgkmcnt(7)
	v_mfma_f32_32x32x16_bf16 v[82:97], v[12:15], v[146:149], v[82:97]
	ds_read_b128 v[242:245], v0 offset:6784
	s_waitcnt lgkmcnt(7)
	v_mfma_f32_32x32x16_bf16 v[82:97], v[214:217], v[126:129], v[82:97]
	ds_read_b128 v[246:249], v0 offset:6816
	s_waitcnt lgkmcnt(7)
	v_mfma_f32_32x32x16_bf16 v[82:97], v[218:221], v[122:125], v[82:97]
	s_waitcnt lgkmcnt(6)
	v_mfma_f32_32x32x16_bf16 v[82:97], v[222:225], v[118:121], v[82:97]
	s_cbranch_scc0 .Lat_m0
	v_add_u32_e32 v3, v205, v208
	v_add_u32_e32 v0, 0x4000, v3
	v_add_u32_e32 v3, 0x3000, v3
	s_waitcnt lgkmcnt(5)
	v_mfma_f32_32x32x16_bf16 v[66:81], v[226:229], v[154:157], v[50:65]
	ds_read2_b64 v[226:229], v3 offset0:128 offset1:130
	s_waitcnt lgkmcnt(5)
	v_mfma_f32_32x32x16_bf16 v[66:81], v[230:233], v[150:153], v[66:81]
	ds_read2_b64 v[230:233], v0 offset0:160 offset1:162
	s_nop 3
	v_exp_f32_e32 v214, v82
	v_exp_f32_e32 v215, v83
	v_exp_f32_e32 v216, v84
	s_waitcnt lgkmcnt(5)
	v_mfma_f32_32x32x16_bf16 v[66:81], v[234:237], v[146:149], v[66:81]
	ds_read2_b64 v[234:237], v3 offset0:132 offset1:134
	v_exp_f32_e32 v217, v85
	v_exp_f32_e32 v218, v86
	v_exp_f32_e32 v219, v87
	s_waitcnt lgkmcnt(5)
	v_mfma_f32_32x32x16_bf16 v[66:81], v[238:241], v[126:129], v[66:81]
	ds_read2_b64 v[238:241], v0 offset0:164 offset1:166
	v_exp_f32_e32 v220, v88
	v_exp_f32_e32 v221, v89
	v_max3_f32 v159, v82, v83, v84
	v_max3_f32 v250, v85, v86, v87
	s_waitcnt lgkmcnt(5)
	v_mfma_f32_32x32x16_bf16 v[66:81], v[242:245], v[122:125], v[66:81]
	ds_read2_b64 v[242:245], v3 offset0:136 offset1:138
	v_exp_f32_e32 v222, v90
	v_exp_f32_e32 v223, v91
	v_exp_f32_e32 v224, v92
	s_waitcnt lgkmcnt(5)
	v_mfma_f32_32x32x16_bf16 v[66:81], v[246:249], v[118:121], v[66:81]
	ds_read2_b64 v[246:249], v0 offset0:168 offset1:170
	s_setprio 0
	v_exp_f32_e32 v225, v93
	v_exp_f32_e32 v12, v94
	v_exp_f32_e32 v13, v95
	v_exp_f32_e32 v14, v96
	v_exp_f32_e32 v15, v97
	v_max3_f32 v159, v159, v88, v89
	v_max3_f32 v250, v250, v90, v91
	v_max3_f32 v159, v159, v92, v93
	v_max3_f32 v250, v250, v94, v95
	v_max3_f32 v159, v159, v96, v97
	s_nop 1
	v_max3_f32 v159, v159, v66, v67
	v_max3_f32 v250, v250, v68, v69
	v_max3_f32 v159, v159, v70, v71
	v_max3_f32 v250, v250, v72, v73
	v_max3_f32 v159, v159, v74, v75
	v_max3_f32 v250, v250, v76, v77
	v_max3_f32 v159, v159, v78, v79
	v_max3_f32 v250, v250, v80, v81
	v_max_f32_e32 v0, v159, v250
	v_mov_b32_e32 v3, v0
	s_nop 1
	v_permlane32_swap_b32_e32 v0, v3
	v_max_f32_e32 v0, v0, v3
	s_nop 0
	v_cmp_lt_f32_e32 vcc, s30, v0
	s_cbranch_vccnz .Lat_r0
.Lat_c0:
	v_cvt_pk_bf16_f32 v4, v214, v215
	v_cvt_pk_bf16_f32 v5, v216, v217
	v_cvt_pk_bf16_f32 v6, v218, v219
	v_cvt_pk_bf16_f32 v7, v220, v221
	v_exp_f32_e32 v66, v66
	v_exp_f32_e32 v67, v67
	s_waitcnt lgkmcnt(4)
	v_mfma_f32_32x32x16_bf16 v[32:47], v[226:229], v[4:7], v[32:47]
	v_mfma_f32_32x32x16_bf16 v[16:31], v[230:233], v[4:7], v[16:31]
	v_cvt_pk_bf16_f32 v8, v222, v223
	v_cvt_pk_bf16_f32 v9, v224, v225
	v_cvt_pk_bf16_f32 v10, v12, v13
	v_cvt_pk_bf16_f32 v11, v14, v15
	v_exp_f32_e32 v68, v68
	v_exp_f32_e32 v69, v69
	v_exp_f32_e32 v70, v70
	v_exp_f32_e32 v71, v71
	s_waitcnt lgkmcnt(2)
	v_mfma_f32_32x32x16_bf16 v[32:47], v[234:237], v[8:11], v[32:47]
	v_mfma_f32_32x32x16_bf16 v[16:31], v[238:241], v[8:11], v[16:31]
	v_add_u32_e32 v3, v205, v208
	v_add_u32_e32 v0, 0x4000, v3
	v_add_u32_e32 v3, 0x3000, v3
	ds_read2_b64 v[226:229], v3 offset0:140 offset1:142
	ds_read2_b64 v[230:233], v0 offset0:172 offset1:174
	v_exp_f32_e32 v72, v72
	v_exp_f32_e32 v73, v73
	v_add_f32_e32 v82, v214, v66
	v_add_f32_e32 v83, v215, v67
	v_add_f32_e32 v84, v216, v68
	v_add_f32_e32 v85, v217, v69
	v_cvt_pk_bf16_f32 v4, v66, v67
	v_cvt_pk_bf16_f32 v5, v68, v69
	v_cvt_pk_bf16_f32 v6, v70, v71
	v_cvt_pk_bf16_f32 v7, v72, v73
	v_exp_f32_e32 v74, v74
	v_exp_f32_e32 v75, v75
	v_exp_f32_e32 v76, v76
	v_exp_f32_e32 v77, v77
	s_waitcnt lgkmcnt(2)
	v_mfma_f32_32x32x16_bf16 v[32:47], v[242:245], v[4:7], v[32:47]
	v_mfma_f32_32x32x16_bf16 v[16:31], v[246:249], v[4:7], v[16:31]
	v_add_f32_e32 v86, v218, v70
	v_add_f32_e32 v87, v219, v71
	v_add_f32_e32 v88, v220, v72
	v_add_f32_e32 v89, v221, v73
	v_exp_f32_e32 v78, v78
	v_exp_f32_e32 v79, v79
	v_exp_f32_e32 v80, v80
	v_exp_f32_e32 v81, v81
	v_add_f32_e32 v251, v82, v83
	v_add_f32_e32 v251, v251, v84
	v_add_f32_e32 v251, v251, v85
	v_add_f32_e32 v251, v251, v86
	v_add_f32_e32 v251, v251, v87
	v_add_f32_e32 v251, v251, v88
	v_add_f32_e32 v251, v251, v89
	v_add_f32_e32 v90, v222, v74
	v_add_f32_e32 v91, v223, v75
	v_add_f32_e32 v92, v224, v76
	v_add_f32_e32 v93, v225, v77
	v_add_f32_e32 v94, v12, v78
	v_add_f32_e32 v95, v13, v79
	v_add_f32_e32 v96, v14, v80
	v_add_f32_e32 v97, v15, v81
	v_cvt_pk_bf16_f32 v8, v74, v75
	v_cvt_pk_bf16_f32 v9, v76, v77
	v_cvt_pk_bf16_f32 v10, v78, v79
	v_cvt_pk_bf16_f32 v11, v80, v81
	s_waitcnt lgkmcnt(0)
	s_nop 1
	v_mfma_f32_32x32x16_bf16 v[32:47], v[226:229], v[8:11], v[32:47]
	v_mfma_f32_32x32x16_bf16 v[16:31], v[230:233], v[8:11], v[16:31]
	v_add_f32_e32 v251, v251, v90
	v_add_f32_e32 v251, v251, v91
	v_add_f32_e32 v251, v251, v92
	v_add_f32_e32 v251, v251, v93
	v_add_f32_e32 v251, v251, v94
	v_add_f32_e32 v251, v251, v95
	v_add_f32_e32 v251, v251, v96
	v_add_f32_e32 v251, v251, v97
	v_add_f32_e32 v48, v48, v251
	s_branch .LBB0_855
; DI float max2f(float a, float b) { float r; asm("v_max_f32_e32 %0, %1, %2" : "=v"(r) : "v"(a), "v"(b)); return r; }
; DI void attn_tile(bool MASK, const LAS unsigned char* Ks, const LAS unsigned char* Vs, const bf16x8 (&qr)[6], f32x16& negm, float& mrun, float& lrun, f32x16& o0, f32x16& o1,
;                                        int kv0, int qrow, int r32, int hi) {
;     ...
;     if (__any(mx > AT_THR)) {
;         const float dm = max2f(mx, 0.f);
;         const float alpha = __builtin_amdgcn_exp2f(-dm);
;         mrun += dm; lrun *= alpha;
; #pragma unroll
;         for (int r = 0; r < 16; ++r) { o0[r] *= alpha; o1[r] *= alpha; p0[r] -= dm; p1[r] -= dm; negm[r] = -mrun; }
;     }
;     float ls = 0.f;
; #pragma unroll
;     for (int r = 0; r < 16; ++r) { p0[r] = __builtin_amdgcn_exp2f(p0[r]); p1[r] = __builtin_amdgcn_exp2f(p1[r]); ls += p0[r] + p1[r]; }
.Lat_r0:
	v_max_f32_e32 v0, v0, v1
	s_nop 0
	v_exp_f32_e64 v4, -v0
	v_add_f32_e32 v2, v2, v0
	v_xor_b32_e32 v50, 0x80000000, v2
	v_pk_add_f32 v[82:83], v[82:83], v[0:1] op_sel_hi:[1,0] neg_lo:[0,1] neg_hi:[0,1]
	v_mul_f32_e32 v48, v48, v4
	v_pk_add_f32 v[66:67], v[66:67], v[0:1] op_sel_hi:[1,0] neg_lo:[0,1] neg_hi:[0,1]
	v_pk_add_f32 v[84:85], v[84:85], v[0:1] op_sel_hi:[1,0] neg_lo:[0,1] neg_hi:[0,1]
	v_pk_add_f32 v[68:69], v[68:69], v[0:1] op_sel_hi:[1,0] neg_lo:[0,1] neg_hi:[0,1]
	v_pk_add_f32 v[86:87], v[86:87], v[0:1] op_sel_hi:[1,0] neg_lo:[0,1] neg_hi:[0,1]
	v_pk_add_f32 v[70:71], v[70:71], v[0:1] op_sel_hi:[1,0] neg_lo:[0,1] neg_hi:[0,1]
	v_pk_add_f32 v[88:89], v[88:89], v[0:1] op_sel_hi:[1,0] neg_lo:[0,1] neg_hi:[0,1]
	v_pk_add_f32 v[72:73], v[72:73], v[0:1] op_sel_hi:[1,0] neg_lo:[0,1] neg_hi:[0,1]
	v_pk_add_f32 v[90:91], v[90:91], v[0:1] op_sel_hi:[1,0] neg_lo:[0,1] neg_hi:[0,1]
	v_pk_add_f32 v[74:75], v[74:75], v[0:1] op_sel_hi:[1,0] neg_lo:[0,1] neg_hi:[0,1]
	v_pk_add_f32 v[92:93], v[92:93], v[0:1] op_sel_hi:[1,0] neg_lo:[0,1] neg_hi:[0,1]
	v_pk_add_f32 v[76:77], v[76:77], v[0:1] op_sel_hi:[1,0] neg_lo:[0,1] neg_hi:[0,1]
	v_pk_add_f32 v[94:95], v[94:95], v[0:1] op_sel_hi:[1,0] neg_lo:[0,1] neg_hi:[0,1]
	v_pk_add_f32 v[78:79], v[78:79], v[0:1] op_sel_hi:[1,0] neg_lo:[0,1] neg_hi:[0,1]
	v_pk_mul_f32 v[46:47], v[46:47], v[4:5] op_sel_hi:[1,0]
	v_pk_mul_f32 v[44:45], v[44:45], v[4:5] op_sel_hi:[1,0]
	v_pk_mul_f32 v[42:43], v[42:43], v[4:5] op_sel_hi:[1,0]
	v_pk_mul_f32 v[40:41], v[40:41], v[4:5] op_sel_hi:[1,0]
	v_pk_mul_f32 v[38:39], v[38:39], v[4:5] op_sel_hi:[1,0]
	v_pk_mul_f32 v[36:37], v[36:37], v[4:5] op_sel_hi:[1,0]
	v_pk_mul_f32 v[34:35], v[34:35], v[4:5] op_sel_hi:[1,0]
	v_pk_mul_f32 v[32:33], v[32:33], v[4:5] op_sel_hi:[1,0]
	v_pk_mul_f32 v[30:31], v[30:31], v[4:5] op_sel_hi:[1,0]
	v_pk_mul_f32 v[28:29], v[28:29], v[4:5] op_sel_hi:[1,0]
	v_pk_mul_f32 v[26:27], v[26:27], v[4:5] op_sel_hi:[1,0]
	v_pk_mul_f32 v[24:25], v[24:25], v[4:5] op_sel_hi:[1,0]
	v_pk_mul_f32 v[22:23], v[22:23], v[4:5] op_sel_hi:[1,0]
	v_pk_mul_f32 v[20:21], v[20:21], v[4:5] op_sel_hi:[1,0]
	v_pk_mul_f32 v[18:19], v[18:19], v[4:5] op_sel_hi:[1,0]
	v_pk_mul_f32 v[16:17], v[16:17], v[4:5] op_sel_hi:[1,0]
	v_pk_add_f32 v[96:97], v[96:97], v[0:1] op_sel_hi:[1,0] neg_lo:[0,1] neg_hi:[0,1]
	v_pk_add_f32 v[80:81], v[80:81], v[0:1] op_sel_hi:[1,0] neg_lo:[0,1] neg_hi:[0,1]
	v_mov_b32_e32 v51, v50
	v_mov_b32_e32 v52, v50
	v_mov_b32_e32 v53, v50
	v_mov_b32_e32 v54, v50
	v_mov_b32_e32 v55, v50
	v_mov_b32_e32 v56, v50
	v_mov_b32_e32 v57, v50
	v_mov_b32_e32 v58, v50
	v_mov_b32_e32 v59, v50
	v_mov_b32_e32 v60, v50
	v_mov_b32_e32 v61, v50
	v_mov_b32_e32 v62, v50
	v_mov_b32_e32 v63, v50
	v_mov_b32_e32 v64, v50
	v_mov_b32_e32 v65, v50
	v_exp_f32_e32 v214, v82
	v_exp_f32_e32 v215, v83
	v_exp_f32_e32 v216, v84
	v_exp_f32_e32 v217, v85
	v_exp_f32_e32 v218, v86
	v_exp_f32_e32 v219, v87
	v_exp_f32_e32 v220, v88
	v_exp_f32_e32 v221, v89
	v_exp_f32_e32 v222, v90
	v_exp_f32_e32 v223, v91
	v_exp_f32_e32 v224, v92
	v_exp_f32_e32 v225, v93
	v_exp_f32_e32 v12, v94
	v_exp_f32_e32 v13, v95
	v_exp_f32_e32 v14, v96
	v_exp_f32_e32 v15, v97
	s_nop 0
	s_branch .Lat_c0
; #define LAS __attribute__((address_space(3)))
; #define MFMA32(a, b, c) __builtin_amdgcn_mfma_f32_32x32x16_bf16((a), (b), (c), 0, 0, 0)
; DI int crow(int r, int hi) { return (r & 3) + 8 * (r >> 2) + 4 * hi; }
; DI void attn_tile(bool MASK, const LAS unsigned char* Ks, const LAS unsigned char* Vs, const bf16x8 (&qr)[6], f32x16& negm, float& mrun, float& lrun, f32x16& o0, f32x16& o1,
;                                        int kv0, int qrow, int r32, int hi) {
;     ...
;         p0 = MFMA32(a0, qr[0], negm); p1 = MFMA32(a1, qr[0], negm);
;     }
; #pragma unroll
;     for (int d0 = 1; d0 < 6; ++d0) {
;         const bf16x8 a0 = *(const LAS bf16x8*)(Ks + r32 * 208 + (2 * d0 + hi) * 16);
;         const bf16x8 a1 = *(const LAS bf16x8*)(Ks + (32 + r32) * 208 + (2 * d0 + hi) * 16);
;         p0 = MFMA32(a0, qr[d0], p0); p1 = MFMA32(a1, qr[d0], p1);
;     }
;     __builtin_amdgcn_s_setprio(0);
;     if (MASK) {
;         asm volatile("" ::: "memory");
; #pragma unroll
;         for (int r = 0; r < 16; ++r) { const int kv = kv0 + crow(r, hi); if (kv > qrow) p0[r] = -INFINITY; if (kv + 32 > qrow) p1[r] = -INFINITY; }
;     }
.Lat_m0:
	s_waitcnt lgkmcnt(5)
	v_mfma_f32_32x32x16_bf16 v[66:81], v[226:229], v[154:157], v[50:65]
	s_waitcnt lgkmcnt(4)
	v_mfma_f32_32x32x16_bf16 v[66:81], v[230:233], v[150:153], v[66:81]
	s_waitcnt lgkmcnt(3)
	v_mfma_f32_32x32x16_bf16 v[66:81], v[234:237], v[146:149], v[66:81]
	s_waitcnt lgkmcnt(2)
	v_mfma_f32_32x32x16_bf16 v[66:81], v[238:241], v[126:129], v[66:81]
	s_waitcnt lgkmcnt(1)
	v_mfma_f32_32x32x16_bf16 v[66:81], v[242:245], v[122:125], v[66:81]
	s_waitcnt lgkmcnt(0)
	v_mfma_f32_32x32x16_bf16 v[66:81], v[246:249], v[118:121], v[66:81]
	s_setprio 0
	v_add_u32_e32 v3, v205, v208
	v_add_u32_e32 v0, 0x4000, v3
	v_add_u32_e32 v3, 0x3000, v3
	ds_read2_b64 v[214:217], v3 offset0:128 offset1:130
	ds_read2_b64 v[218:221], v0 offset0:160 offset1:162
	ds_read2_b64 v[222:225], v3 offset0:132 offset1:134
	ds_read2_b64 v[226:229], v0 offset0:164 offset1:166
	ds_read2_b64 v[230:233], v3 offset0:136 offset1:138
	ds_read2_b64 v[234:237], v0 offset0:168 offset1:170
	ds_read2_b64 v[238:241], v3 offset0:140 offset1:142
	ds_read2_b64 v[242:245], v0 offset0:172 offset1:174
	v_add_u32_e32 v0, s21, v207
	v_add_u32_e32 v3, 32, v0
	v_cmp_le_i32_e32 vcc, v3, v49
	v_add_u32_e32 v3, 33, v0
	s_nop 5
	v_cndmask_b32_e32 v66, v212, v66, vcc
	v_cmp_lt_i32_e32 vcc, v0, v49
	s_nop 1
	v_cndmask_b32_e32 v83, v212, v83, vcc
	v_cmp_le_i32_e32 vcc, v0, v49
	s_nop 1
	v_cndmask_b32_e32 v82, v212, v82, vcc
	v_cmp_le_i32_e32 vcc, v3, v49
	v_add_u32_e32 v3, 2, v0
	s_nop 0
	v_cndmask_b32_e32 v67, v212, v67, vcc
	v_cmp_le_i32_e32 vcc, v3, v49
	v_add_u32_e32 v3, 34, v0
	s_nop 0
	v_cndmask_b32_e32 v84, v212, v84, vcc
	v_cmp_le_i32_e32 vcc, v3, v49
	v_add_u32_e32 v3, 3, v0
	s_nop 0
	v_cndmask_b32_e32 v68, v212, v68, vcc
	v_cmp_le_i32_e32 vcc, v3, v49
	v_add_u32_e32 v3, 35, v0
	s_nop 0
	v_cndmask_b32_e32 v85, v212, v85, vcc
	v_cmp_le_i32_e32 vcc, v3, v49
	v_add_u32_e32 v3, 8, v0
	s_nop 0
	v_cndmask_b32_e32 v69, v212, v69, vcc
	v_cmp_le_i32_e32 vcc, v3, v49
	v_add_u32_e32 v3, 40, v0
	s_nop 0
	v_cndmask_b32_e32 v86, v212, v86, vcc
	v_cmp_le_i32_e32 vcc, v3, v49
	v_add_u32_e32 v3, 9, v0
	s_nop 0
	v_cndmask_b32_e32 v70, v212, v70, vcc
	v_cmp_le_i32_e32 vcc, v3, v49
	v_add_u32_e32 v3, 41, v0
	s_nop 0
	v_cndmask_b32_e32 v87, v212, v87, vcc
	v_cmp_le_i32_e32 vcc, v3, v49
	v_add_u32_e32 v3, 10, v0
	s_nop 0
	v_cndmask_b32_e32 v71, v212, v71, vcc
	v_cmp_le_i32_e32 vcc, v3, v49
	v_add_u32_e32 v3, 42, v0
	s_nop 0
	v_cndmask_b32_e32 v88, v212, v88, vcc
	v_cmp_le_i32_e32 vcc, v3, v49
	v_add_u32_e32 v3, 11, v0
	s_nop 0
	v_cndmask_b32_e32 v72, v212, v72, vcc
	v_cmp_le_i32_e32 vcc, v3, v49
	v_add_u32_e32 v3, 43, v0
	s_nop 0
	v_cndmask_b32_e32 v89, v212, v89, vcc
	v_cmp_le_i32_e32 vcc, v3, v49
	v_add_u32_e32 v3, 16, v0
	s_nop 0
	v_cndmask_b32_e32 v73, v212, v73, vcc
	v_cmp_le_i32_e32 vcc, v3, v49
	v_add_u32_e32 v3, 48, v0
	s_nop 0
	v_cndmask_b32_e32 v90, v212, v90, vcc
	v_cmp_le_i32_e32 vcc, v3, v49
	v_add_u32_e32 v3, 17, v0
	s_nop 0
	v_cndmask_b32_e32 v74, v212, v74, vcc
	v_cmp_le_i32_e32 vcc, v3, v49
	v_add_u32_e32 v3, 49, v0
	s_nop 0
	v_cndmask_b32_e32 v91, v212, v91, vcc
	v_cmp_le_i32_e32 vcc, v3, v49
	v_add_u32_e32 v3, 18, v0
	s_nop 0
	v_cndmask_b32_e32 v75, v212, v75, vcc
	v_cmp_le_i32_e32 vcc, v3, v49
	v_add_u32_e32 v3, 50, v0
	s_nop 0
	v_cndmask_b32_e32 v92, v212, v92, vcc
	v_cmp_le_i32_e32 vcc, v3, v49
	v_add_u32_e32 v3, 19, v0
	s_nop 0
	v_cndmask_b32_e32 v76, v212, v76, vcc
	v_cmp_le_i32_e32 vcc, v3, v49
	v_add_u32_e32 v3, 51, v0
	s_nop 0
	v_cndmask_b32_e32 v93, v212, v93, vcc
	v_cmp_le_i32_e32 vcc, v3, v49
	v_add_u32_e32 v3, 24, v0
	s_nop 0
	v_cndmask_b32_e32 v77, v212, v77, vcc
	v_cmp_le_i32_e32 vcc, v3, v49
	v_add_u32_e32 v3, 56, v0
	s_nop 0
	v_cndmask_b32_e32 v94, v212, v94, vcc
	v_cmp_le_i32_e32 vcc, v3, v49
	v_add_u32_e32 v3, 25, v0
	s_nop 0
	v_cndmask_b32_e32 v78, v212, v78, vcc
	v_cmp_le_i32_e32 vcc, v3, v49
	v_add_u32_e32 v3, 57, v0
	s_nop 0
	v_cndmask_b32_e32 v95, v212, v95, vcc
	v_cmp_le_i32_e32 vcc, v3, v49
	v_add_u32_e32 v3, 26, v0
	s_nop 0
	v_cndmask_b32_e32 v79, v212, v79, vcc
	v_cmp_le_i32_e32 vcc, v3, v49
	v_add_u32_e32 v3, 58, v0
	s_nop 0
	v_cndmask_b32_e32 v96, v212, v96, vcc
	v_cmp_le_i32_e32 vcc, v3, v49
	v_add_u32_e32 v3, 27, v0
	v_add_u32_e32 v0, 59, v0
	v_cndmask_b32_e32 v80, v212, v80, vcc
	v_cmp_le_i32_e32 vcc, v3, v49
	s_nop 1
	v_cndmask_b32_e32 v97, v212, v97, vcc
	v_cmp_le_i32_e32 vcc, v0, v49
	s_nop 1
	v_cndmask_b32_e32 v81, v212, v81, vcc

; DI void attn_tile(bool MASK, const LAS unsigned char* Ks, const LAS unsigned char* Vs, const bf16x8 (&qr)[6], f32x16& negm, float& mrun, float& lrun, f32x16& o0, f32x16& o1,
;                                        int kv0, int qrow, int r32, int hi) {
;     ...
;     __builtin_amdgcn_s_setprio(1);
;     {
;         const bf16x8 a0 = *(const LAS bf16x8*)(Ks + r32 * 208 + hi * 16);
;         const bf16x8 a1 = *(const LAS bf16x8*)(Ks + (32 + r32) * 208 + hi * 16);
;         p0 = MFMA32(a0, qr[0], negm); p1 = MFMA32(a1, qr[0], negm);
;     }
; #pragma unroll
;     for (int d0 = 1; d0 < 6; ++d0) {
;         const bf16x8 a0 = *(const LAS bf16x8*)(Ks + r32 * 208 + (2 * d0 + hi) * 16);
;         const bf16x8 a1 = *(const LAS bf16x8*)(Ks + (32 + r32) * 208 + (2 * d0 + hi) * 16);
;         p0 = MFMA32(a0, qr[d0], p0); p1 = MFMA32(a1, qr[d0], p1);
;     }
;     __builtin_amdgcn_s_setprio(0);
;     if (MASK) {
;         asm volatile("" ::: "memory");
; #pragma unroll
;         for (int r = 0; r < 16; ++r) { const int kv = kv0 + crow(r, hi); if (kv > qrow) p0[r] = -INFINITY; if (kv + 32 > qrow) p1[r] = -INFINITY; }
;     }
;     float mxa = max3f(p0[0], p0[1], p1[0]), mxb = max3f(p0[2], p0[3], p1[1]); mxa = max3f(mxa, p1[2], p1[3]);
; #pragma unroll
;     for (int r = 4; r < 16; r += 4) { mxa = max3f(mxa, p0[r], p0[r + 1]); mxb = max3f(mxb, p0[r + 2], p0[r + 3]); mxa = max3f(mxa, p1[r], p1[r + 1]); mxb = max3f(mxb, p1[r + 2], p1[r + 3]); }
;     float mx = max2f(mxa, mxb);
;     mx = max2f(mx, __shfl_xor(mx, 32));
;     if (__any(mx > AT_THR)) {
;         const float dm = max2f(mx, 0.f);
;         const float alpha = __builtin_amdgcn_exp2f(-dm);
;         mrun += dm; lrun *= alpha;
; #pragma unroll
;         for (int r = 0; r < 16; ++r) { o0[r] *= alpha; o1[r] *= alpha; p0[r] -= dm; p1[r] -= dm; negm[r] = -mrun; }
;     }
;     float ls = 0.f;
; #pragma unroll
;     for (int r = 0; r < 16; ++r) { p0[r] = __builtin_amdgcn_exp2f(p0[r]); p1[r] = __builtin_amdgcn_exp2f(p1[r]); ls += p0[r] + p1[r]; }
;     lrun += ls;
; #pragma unroll
;     for (int ks = 0; ks < 4; ++ks) {
;         u32x4 pp;
;         if (ks == 0) { pp.x = pk2(p0[0], p0[1]); pp.y = pk2(p0[2], p0[3]); pp.z = pk2(p0[4], p0[5]); pp.w = pk2(p0[6], p0[7]); }
;         else if (ks == 1) { pp.x = pk2(p0[8], p0[9]); pp.y = pk2(p0[10], p0[11]); pp.z = pk2(p0[12], p0[13]); pp.w = pk2(p0[14], p0[15]); }
.LBB0_855:
	s_add_i32 s33, s23, 5
	s_min_i32 s33, s33, s20
	v_mad_i64_i32 v[4:5], s[34:35], s33, v161, v[190:191]
	v_mad_i64_i32 v[6:7], s[34:35], s33, v161, v[194:195]
	v_add3_u32 v0, v204, v199, s31
	s_lshl_b32 s34, s33, 6
	s_waitcnt lgkmcnt(0)
	s_barrier
	ds_write_b128 v209, v[98:101] offset:44032
	ds_write_b128 v210, v[102:105] offset:44032
	ds_write2_b64 v0, v[114:115], v[116:117] offset1:1
	s_ashr_i32 s35, s34, 31
	global_load_dwordx4 v[98:101], v[4:5], off
	global_load_dwordx4 v[102:105], v[6:7], off
	v_lshl_add_u64 v[4:5], s[34:35], 1, v[192:193]
	global_load_dwordx4 v[114:117], v[4:5], off
	s_add_i32 s33, s23, 1
	s_cmp_ge_i32 s33, s19
	s_cbranch_scc1 .LBB0_862
	s_add_i32 s34, s21, 64
	s_cmp_gt_i32 s34, s22
	s_cbranch_scc1 .LBB0_862
	s_cmp_lt_i32 s33, s12
	s_setprio 1
	v_add_u32_e32 v0, v206, v160
	ds_read_b128 v[4:7], v0 offset:22016
	ds_read_b128 v[8:11], v0 offset:22048
	ds_read_b128 v[12:15], v0 offset:22080
	ds_read_b128 v[214:217], v0 offset:22112
	ds_read_b128 v[218:221], v0 offset:22144
	ds_read_b128 v[222:225], v0 offset:22176
	ds_read_b128 v[226:229], v0 offset:28672
	ds_read_b128 v[230:233], v0 offset:28704
	s_waitcnt lgkmcnt(7)
	v_mfma_f32_32x32x16_bf16 v[82:97], v[4:7], v[154:157], v[50:65]
	ds_read_b128 v[234:237], v0 offset:28736
	s_waitcnt lgkmcnt(7)
	v_mfma_f32_32x32x16_bf16 v[82:97], v[8:11], v[150:153], v[82:97]
	ds_read_b128 v[238:241], v0 offset:28768
	s_waitcnt lgkmcnt(7)
	v_mfma_f32_32x32x16_bf16 v[82:97], v[12:15], v[146:149], v[82:97]
	ds_read_b128 v[242:245], v0 offset:28800
	s_waitcnt lgkmcnt(7)
	v_mfma_f32_32x32x16_bf16 v[82:97], v[214:217], v[126:129], v[82:97]
	ds_read_b128 v[246:249], v0 offset:28832
	s_waitcnt lgkmcnt(7)
	v_mfma_f32_32x32x16_bf16 v[82:97], v[218:221], v[122:125], v[82:97]
	s_waitcnt lgkmcnt(6)
	v_mfma_f32_32x32x16_bf16 v[82:97], v[222:225], v[118:121], v[82:97]
	s_cbranch_scc0 .Lat_m1
	v_add_u32_e32 v3, v205, v208
	v_add_u32_e32 v0, 0x9800, v3
	v_add_u32_e32 v3, 0x8800, v3
	s_waitcnt lgkmcnt(5)
	v_mfma_f32_32x32x16_bf16 v[66:81], v[226:229], v[154:157], v[50:65]
	ds_read2_b64 v[226:229], v3 offset0:64 offset1:66
	s_waitcnt lgkmcnt(5)
	v_mfma_f32_32x32x16_bf16 v[66:81], v[230:233], v[150:153], v[66:81]
	ds_read2_b64 v[230:233], v0 offset0:96 offset1:98
	s_nop 3
	v_exp_f32_e32 v214, v82
	v_exp_f32_e32 v215, v83
	v_exp_f32_e32 v216, v84
	s_waitcnt lgkmcnt(5)
	v_mfma_f32_32x32x16_bf16 v[66:81], v[234:237], v[146:149], v[66:81]
	ds_read2_b64 v[234:237], v3 offset0:68 offset1:70
	v_exp_f32_e32 v217, v85
	v_exp_f32_e32 v218, v86
	v_exp_f32_e32 v219, v87
	s_waitcnt lgkmcnt(5)
	v_mfma_f32_32x32x16_bf16 v[66:81], v[238:241], v[126:129], v[66:81]
	ds_read2_b64 v[238:241], v0 offset0:100 offset1:102
	v_exp_f32_e32 v220, v88
	v_exp_f32_e32 v221, v89
	v_max3_f32 v159, v82, v83, v84
	v_max3_f32 v250, v85, v86, v87
	s_waitcnt lgkmcnt(5)
	v_mfma_f32_32x32x16_bf16 v[66:81], v[242:245], v[122:125], v[66:81]
	ds_read2_b64 v[242:245], v3 offset0:72 offset1:74
	v_exp_f32_e32 v222, v90
	v_exp_f32_e32 v223, v91
	v_exp_f32_e32 v224, v92
	s_waitcnt lgkmcnt(5)
	v_mfma_f32_32x32x16_bf16 v[66:81], v[246:249], v[118:121], v[66:81]
	ds_read2_b64 v[246:249], v0 offset0:104 offset1:106
	s_setprio 0
	v_exp_f32_e32 v225, v93
	v_exp_f32_e32 v12, v94
	v_exp_f32_e32 v13, v95
	v_exp_f32_e32 v14, v96
	v_exp_f32_e32 v15, v97
	v_max3_f32 v159, v159, v88, v89
	v_max3_f32 v250, v250, v90, v91
	v_max3_f32 v159, v159, v92, v93
	v_max3_f32 v250, v250, v94, v95
	v_max3_f32 v159, v159, v96, v97
	s_nop 1
	v_max3_f32 v159, v159, v66, v67
	v_max3_f32 v250, v250, v68, v69
	v_max3_f32 v159, v159, v70, v71
	v_max3_f32 v250, v250, v72, v73
	v_max3_f32 v159, v159, v74, v75
	v_max3_f32 v250, v250, v76, v77
	v_max3_f32 v159, v159, v78, v79
	v_max3_f32 v250, v250, v80, v81
	v_max_f32_e32 v0, v159, v250
	v_mov_b32_e32 v3, v0
	s_nop 1
	v_permlane32_swap_b32_e32 v0, v3
	v_max_f32_e32 v0, v0, v3
	s_nop 0
	v_cmp_lt_f32_e32 vcc, s30, v0
	s_cbranch_vccnz .Lat_r1
.Lat_c1:
	v_cvt_pk_bf16_f32 v4, v214, v215
	v_cvt_pk_bf16_f32 v5, v216, v217
	v_cvt_pk_bf16_f32 v6, v218, v219
	v_cvt_pk_bf16_f32 v7, v220, v221
	v_exp_f32_e32 v66, v66
	v_exp_f32_e32 v67, v67
	s_waitcnt lgkmcnt(4)
	v_mfma_f32_32x32x16_bf16 v[32:47], v[226:229], v[4:7], v[32:47]
	v_mfma_f32_32x32x16_bf16 v[16:31], v[230:233], v[4:7], v[16:31]
	v_cvt_pk_bf16_f32 v8, v222, v223
	v_cvt_pk_bf16_f32 v9, v224, v225
	v_cvt_pk_bf16_f32 v10, v12, v13
	v_cvt_pk_bf16_f32 v11, v14, v15
	v_exp_f32_e32 v68, v68
	v_exp_f32_e32 v69, v69
	v_exp_f32_e32 v70, v70
	v_exp_f32_e32 v71, v71
	s_waitcnt lgkmcnt(2)
	v_mfma_f32_32x32x16_bf16 v[32:47], v[234:237], v[8:11], v[32:47]
	v_mfma_f32_32x32x16_bf16 v[16:31], v[238:241], v[8:11], v[16:31]
	v_add_u32_e32 v3, v205, v208
	v_add_u32_e32 v0, 0x9800, v3
	v_add_u32_e32 v3, 0x8800, v3
	ds_read2_b64 v[226:229], v3 offset0:76 offset1:78
	ds_read2_b64 v[230:233], v0 offset0:108 offset1:110
	v_exp_f32_e32 v72, v72
	v_exp_f32_e32 v73, v73
	v_add_f32_e32 v82, v214, v66
	v_add_f32_e32 v83, v215, v67
	v_add_f32_e32 v84, v216, v68
	v_add_f32_e32 v85, v217, v69
	v_cvt_pk_bf16_f32 v4, v66, v67
	v_cvt_pk_bf16_f32 v5, v68, v69
	v_cvt_pk_bf16_f32 v6, v70, v71
	v_cvt_pk_bf16_f32 v7, v72, v73
	v_exp_f32_e32 v74, v74
	v_exp_f32_e32 v75, v75
	v_exp_f32_e32 v76, v76
	v_exp_f32_e32 v77, v77
	s_waitcnt lgkmcnt(2)
	v_mfma_f32_32x32x16_bf16 v[32:47], v[242:245], v[4:7], v[32:47]
	v_mfma_f32_32x32x16_bf16 v[16:31], v[246:249], v[4:7], v[16:31]
	v_add_f32_e32 v86, v218, v70
	v_add_f32_e32 v87, v219, v71
	v_add_f32_e32 v88, v220, v72
	v_add_f32_e32 v89, v221, v73
	v_exp_f32_e32 v78, v78
	v_exp_f32_e32 v79, v79
	v_exp_f32_e32 v80, v80
	v_exp_f32_e32 v81, v81
	v_add_f32_e32 v251, v82, v83
	v_add_f32_e32 v251, v251, v84
	v_add_f32_e32 v251, v251, v85
	v_add_f32_e32 v251, v251, v86
	v_add_f32_e32 v251, v251, v87
	v_add_f32_e32 v251, v251, v88
	v_add_f32_e32 v251, v251, v89
	v_add_f32_e32 v90, v222, v74
	v_add_f32_e32 v91, v223, v75
	v_add_f32_e32 v92, v224, v76
	v_add_f32_e32 v93, v225, v77
	v_add_f32_e32 v94, v12, v78
	v_add_f32_e32 v95, v13, v79
	v_add_f32_e32 v96, v14, v80
	v_add_f32_e32 v97, v15, v81
	v_cvt_pk_bf16_f32 v8, v74, v75
	v_cvt_pk_bf16_f32 v9, v76, v77
	v_cvt_pk_bf16_f32 v10, v78, v79
	v_cvt_pk_bf16_f32 v11, v80, v81
	s_waitcnt lgkmcnt(0)
	s_nop 1
	v_mfma_f32_32x32x16_bf16 v[32:47], v[226:229], v[8:11], v[32:47]
	v_mfma_f32_32x32x16_bf16 v[16:31], v[230:233], v[8:11], v[16:31]
	v_add_f32_e32 v251, v251, v90
	v_add_f32_e32 v251, v251, v91
	v_add_f32_e32 v251, v251, v92
	v_add_f32_e32 v251, v251, v93
	v_add_f32_e32 v251, v251, v94
	v_add_f32_e32 v251, v251, v95
	v_add_f32_e32 v251, v251, v96
	v_add_f32_e32 v251, v251, v97
	v_add_f32_e32 v48, v48, v251
	s_branch .LBB0_862

; #define LAS __attribute__((address_space(3)))
; #define MFMA32(a, b, c) __builtin_amdgcn_mfma_f32_32x32x16_bf16((a), (b), (c), 0, 0, 0)
; DI int crow(int r, int hi) { return (r & 3) + 8 * (r >> 2) + 4 * hi; }
; DI void attn_tile(bool MASK, const LAS unsigned char* Ks, const LAS unsigned char* Vs, const bf16x8 (&qr)[6], f32x16& negm, float& mrun, float& lrun, f32x16& o0, f32x16& o1,
;                                        int kv0, int qrow, int r32, int hi) {
;     ...
;         p0 = MFMA32(a0, qr[0], negm); p1 = MFMA32(a1, qr[0], negm);
;     }
; #pragma unroll
;     for (int d0 = 1; d0 < 6; ++d0) {
;         const bf16x8 a0 = *(const LAS bf16x8*)(Ks + r32 * 208 + (2 * d0 + hi) * 16);
;         const bf16x8 a1 = *(const LAS bf16x8*)(Ks + (32 + r32) * 208 + (2 * d0 + hi) * 16);
;         p0 = MFMA32(a0, qr[d0], p0); p1 = MFMA32(a1, qr[d0], p1);
;     }
;     __builtin_amdgcn_s_setprio(0);
;     if (MASK) {
;         asm volatile("" ::: "memory");
; #pragma unroll
;         for (int r = 0; r < 16; ++r) { const int kv = kv0 + crow(r, hi); if (kv > qrow) p0[r] = -INFINITY; if (kv + 32 > qrow) p1[r] = -INFINITY; }
;     }
.Lat_m1:
	s_waitcnt lgkmcnt(5)
	v_mfma_f32_32x32x16_bf16 v[66:81], v[226:229], v[154:157], v[50:65]
	s_waitcnt lgkmcnt(4)
	v_mfma_f32_32x32x16_bf16 v[66:81], v[230:233], v[150:153], v[66:81]
	s_waitcnt lgkmcnt(3)
	v_mfma_f32_32x32x16_bf16 v[66:81], v[234:237], v[146:149], v[66:81]
	s_waitcnt lgkmcnt(2)
	v_mfma_f32_32x32x16_bf16 v[66:81], v[238:241], v[126:129], v[66:81]
	s_waitcnt lgkmcnt(1)
	v_mfma_f32_32x32x16_bf16 v[66:81], v[242:245], v[122:125], v[66:81]
	s_waitcnt lgkmcnt(0)
	v_mfma_f32_32x32x16_bf16 v[66:81], v[246:249], v[118:121], v[66:81]
	s_setprio 0
	v_add_u32_e32 v3, v205, v208
	v_add_u32_e32 v0, 0x9800, v3
	v_add_u32_e32 v3, 0x8800, v3
	ds_read2_b64 v[214:217], v3 offset0:64 offset1:66
	ds_read2_b64 v[218:221], v0 offset0:96 offset1:98
	ds_read2_b64 v[222:225], v3 offset0:68 offset1:70
	ds_read2_b64 v[226:229], v0 offset0:100 offset1:102
	ds_read2_b64 v[230:233], v3 offset0:72 offset1:74
	ds_read2_b64 v[234:237], v0 offset0:104 offset1:106
	ds_read2_b64 v[238:241], v3 offset0:76 offset1:78
	ds_read2_b64 v[242:245], v0 offset0:108 offset1:110
	v_add_u32_e32 v0, s21, v207
	v_add_u32_e32 v4, 0x60, v0
	v_add_u32_e32 v3, 64, v0
	v_cmp_le_i32_e32 vcc, v4, v49
	s_nop 5
	v_cndmask_b32_e32 v66, v212, v66, vcc
	v_cmp_lt_i32_e32 vcc, v3, v49
	s_nop 1
	v_cndmask_b32_e32 v83, v212, v83, vcc
	v_cmp_le_i32_e32 vcc, v3, v49
	v_add_u32_e32 v3, 0x61, v0
	s_nop 0
	v_cndmask_b32_e32 v82, v212, v82, vcc
	v_cmp_le_i32_e32 vcc, v3, v49
	v_add_u32_e32 v3, 0x42, v0
	s_nop 0
	v_cndmask_b32_e32 v67, v212, v67, vcc
	v_cmp_le_i32_e32 vcc, v3, v49
	v_add_u32_e32 v3, 0x62, v0
	s_nop 0
	v_cndmask_b32_e32 v84, v212, v84, vcc
	v_cmp_le_i32_e32 vcc, v3, v49
	v_add_u32_e32 v3, 0x43, v0
	s_nop 0
	v_cndmask_b32_e32 v68, v212, v68, vcc
	v_cmp_le_i32_e32 vcc, v3, v49
	v_add_u32_e32 v3, 0x63, v0
	s_nop 0
	v_cndmask_b32_e32 v85, v212, v85, vcc
	v_cmp_le_i32_e32 vcc, v3, v49
	v_add_u32_e32 v3, 0x48, v0
	s_nop 0
	v_cndmask_b32_e32 v69, v212, v69, vcc
	v_cmp_le_i32_e32 vcc, v3, v49
	v_add_u32_e32 v3, 0x68, v0
	s_nop 0
	v_cndmask_b32_e32 v86, v212, v86, vcc
	v_cmp_le_i32_e32 vcc, v3, v49
	v_add_u32_e32 v3, 0x49, v0
	s_nop 0
	v_cndmask_b32_e32 v70, v212, v70, vcc
	v_cmp_le_i32_e32 vcc, v3, v49
	v_add_u32_e32 v3, 0x69, v0
	s_nop 0
	v_cndmask_b32_e32 v87, v212, v87, vcc
	v_cmp_le_i32_e32 vcc, v3, v49
	v_add_u32_e32 v3, 0x4a, v0
	s_nop 0
	v_cndmask_b32_e32 v71, v212, v71, vcc
	v_cmp_le_i32_e32 vcc, v3, v49
	v_add_u32_e32 v3, 0x6a, v0
	s_nop 0
	v_cndmask_b32_e32 v88, v212, v88, vcc
	v_cmp_le_i32_e32 vcc, v3, v49
	v_add_u32_e32 v3, 0x4b, v0
	s_nop 0
	v_cndmask_b32_e32 v72, v212, v72, vcc
	v_cmp_le_i32_e32 vcc, v3, v49
	v_add_u32_e32 v3, 0x6b, v0
	s_nop 0
	v_cndmask_b32_e32 v89, v212, v89, vcc
	v_cmp_le_i32_e32 vcc, v3, v49
	v_add_u32_e32 v3, 0x50, v0
	s_nop 0
	v_cndmask_b32_e32 v73, v212, v73, vcc
	v_cmp_le_i32_e32 vcc, v3, v49
	v_add_u32_e32 v3, 0x70, v0
	s_nop 0
	v_cndmask_b32_e32 v90, v212, v90, vcc
	v_cmp_le_i32_e32 vcc, v3, v49
	v_add_u32_e32 v3, 0x51, v0
	s_nop 0
	v_cndmask_b32_e32 v74, v212, v74, vcc
	v_cmp_le_i32_e32 vcc, v3, v49
	v_add_u32_e32 v3, 0x71, v0
	s_nop 0
	v_cndmask_b32_e32 v91, v212, v91, vcc
	v_cmp_le_i32_e32 vcc, v3, v49
	v_add_u32_e32 v3, 0x52, v0
	s_nop 0
	v_cndmask_b32_e32 v75, v212, v75, vcc
	v_cmp_le_i32_e32 vcc, v3, v49
	v_add_u32_e32 v3, 0x72, v0
	s_nop 0
	v_cndmask_b32_e32 v92, v212, v92, vcc
	v_cmp_le_i32_e32 vcc, v3, v49
	v_add_u32_e32 v3, 0x53, v0
	s_nop 0
	v_cndmask_b32_e32 v76, v212, v76, vcc
	v_cmp_le_i32_e32 vcc, v3, v49
	v_add_u32_e32 v3, 0x73, v0
	s_nop 0
	v_cndmask_b32_e32 v93, v212, v93, vcc
	v_cmp_le_i32_e32 vcc, v3, v49
	v_add_u32_e32 v3, 0x58, v0
	s_nop 0
	v_cndmask_b32_e32 v77, v212, v77, vcc
	v_cmp_le_i32_e32 vcc, v3, v49
	v_add_u32_e32 v3, 0x78, v0
	s_nop 0
	v_cndmask_b32_e32 v94, v212, v94, vcc
	v_cmp_le_i32_e32 vcc, v3, v49
	v_add_u32_e32 v3, 0x59, v0
	s_nop 0
	v_cndmask_b32_e32 v78, v212, v78, vcc
	v_cmp_le_i32_e32 vcc, v3, v49
	v_add_u32_e32 v3, 0x79, v0
	s_nop 0
	v_cndmask_b32_e32 v95, v212, v95, vcc
	v_cmp_le_i32_e32 vcc, v3, v49
	v_add_u32_e32 v3, 0x5a, v0
	s_nop 0
	v_cndmask_b32_e32 v79, v212, v79, vcc
	v_cmp_le_i32_e32 vcc, v3, v49
	v_add_u32_e32 v3, 0x7a, v0
	s_nop 0
	v_cndmask_b32_e32 v96, v212, v96, vcc
	v_cmp_le_i32_e32 vcc, v3, v49
	v_add_u32_e32 v3, 0x5b, v0
	v_add_u32_e32 v0, 0x7b, v0
	v_cndmask_b32_e32 v80, v212, v80, vcc
	v_cmp_le_i32_e32 vcc, v3, v49
	s_nop 1
	v_cndmask_b32_e32 v97, v212, v97, vcc
	v_cmp_le_i32_e32 vcc, v0, v49
	s_nop 1
	v_cndmask_b32_e32 v81, v212, v81, vcc

; DI void attn_tile(bool MASK, const LAS unsigned char* Ks, const LAS unsigned char* Vs, const bf16x8 (&qr)[6], f32x16& negm, float& mrun, float& lrun, f32x16& o0, f32x16& o1,
;                                        int kv0, int qrow, int r32, int hi) {
;     ...
;     __builtin_amdgcn_s_setprio(1);
;     {
;         const bf16x8 a0 = *(const LAS bf16x8*)(Ks + r32 * 208 + hi * 16);
;         const bf16x8 a1 = *(const LAS bf16x8*)(Ks + (32 + r32) * 208 + hi * 16);
;         p0 = MFMA32(a0, qr[0], negm); p1 = MFMA32(a1, qr[0], negm);
;     }
; #pragma unroll
;     for (int d0 = 1; d0 < 6; ++d0) {
;         const bf16x8 a0 = *(const LAS bf16x8*)(Ks + r32 * 208 + (2 * d0 + hi) * 16);
;         const bf16x8 a1 = *(const LAS bf16x8*)(Ks + (32 + r32) * 208 + (2 * d0 + hi) * 16);
;         p0 = MFMA32(a0, qr[d0], p0); p1 = MFMA32(a1, qr[d0], p1);
;     }
;     __builtin_amdgcn_s_setprio(0);
;     if (MASK) {
;         asm volatile("" ::: "memory");
; #pragma unroll
;         for (int r = 0; r < 16; ++r) { const int kv = kv0 + crow(r, hi); if (kv > qrow) p0[r] = -INFINITY; if (kv + 32 > qrow) p1[r] = -INFINITY; }
;     }
;     float mxa = max3f(p0[0], p0[1], p1[0]), mxb = max3f(p0[2], p0[3], p1[1]); mxa = max3f(mxa, p1[2], p1[3]);
; #pragma unroll
;     for (int r = 4; r < 16; r += 4) { mxa = max3f(mxa, p0[r], p0[r + 1]); mxb = max3f(mxb, p0[r + 2], p0[r + 3]); mxa = max3f(mxa, p1[r], p1[r + 1]); mxb = max3f(mxb, p1[r + 2], p1[r + 3]); }
;     float mx = max2f(mxa, mxb);
;     mx = max2f(mx, __shfl_xor(mx, 32));
;     if (__any(mx > AT_THR)) {
;         const float dm = max2f(mx, 0.f);
;         const float alpha = __builtin_amdgcn_exp2f(-dm);
;         mrun += dm; lrun *= alpha;
; #pragma unroll
;         for (int r = 0; r < 16; ++r) { o0[r] *= alpha; o1[r] *= alpha; p0[r] -= dm; p1[r] -= dm; negm[r] = -mrun; }
;     }
;     float ls = 0.f;
; #pragma unroll
;     for (int r = 0; r < 16; ++r) { p0[r] = __builtin_amdgcn_exp2f(p0[r]); p1[r] = __builtin_amdgcn_exp2f(p1[r]); ls += p0[r] + p1[r]; }
;     lrun += ls;
; #pragma unroll
;     for (int ks = 0; ks < 4; ++ks) {
;         u32x4 pp;
;         if (ks == 0) { pp.x = pk2(p0[0], p0[1]); pp.y = pk2(p0[2], p0[3]); pp.z = pk2(p0[4], p0[5]); pp.w = pk2(p0[6], p0[7]); }
;         else if (ks == 1) { pp.x = pk2(p0[8], p0[9]); pp.y = pk2(p0[10], p0[11]); pp.z = pk2(p0[12], p0[13]); pp.w = pk2(p0[14], p0[15]); }
.LBB0_862:
	s_add_i32 s33, s23, 6
	s_min_i32 s33, s33, s20
	v_mad_i64_i32 v[4:5], s[34:35], s33, v161, v[190:191]
	v_mad_i64_i32 v[6:7], s[34:35], s33, v161, v[194:195]
	s_lshl_b32 s34, s33, 6
	s_waitcnt lgkmcnt(0)
	s_barrier
	s_waitcnt vmcnt(6)
	ds_write_b128 v209, v[142:145]
	ds_write_b128 v210, v[138:141]
	ds_write2_b64 v211, v[134:135], v[136:137] offset1:1
	s_ashr_i32 s35, s34, 31
	global_load_dwordx4 v[142:145], v[4:5], off
	global_load_dwordx4 v[138:141], v[6:7], off
	v_lshl_add_u64 v[4:5], s[34:35], 1, v[192:193]
	global_load_dwordx4 v[134:137], v[4:5], off
	s_add_i32 s33, s23, 2
	s_cmp_ge_i32 s33, s19
	s_cbranch_scc1 .LBB0_848
	s_add_i32 s34, s21, 0x80
	s_cmp_gt_i32 s34, s22
	s_cbranch_scc1 .LBB0_848
	s_cmp_lt_i32 s33, s12
	s_setprio 1
	v_add_u32_e32 v0, v206, v160
	ds_read_b128 v[4:7], v0 offset:44032
	ds_read_b128 v[8:11], v0 offset:44064
	ds_read_b128 v[12:15], v0 offset:44096
	ds_read_b128 v[214:217], v0 offset:44128
	ds_read_b128 v[218:221], v0 offset:44160
	ds_read_b128 v[222:225], v0 offset:44192
	ds_read_b128 v[226:229], v0 offset:50688
	ds_read_b128 v[230:233], v0 offset:50720
	s_waitcnt lgkmcnt(7)
	v_mfma_f32_32x32x16_bf16 v[82:97], v[4:7], v[154:157], v[50:65]
	ds_read_b128 v[234:237], v0 offset:50752
	s_waitcnt lgkmcnt(7)
	v_mfma_f32_32x32x16_bf16 v[82:97], v[8:11], v[150:153], v[82:97]
	ds_read_b128 v[238:241], v0 offset:50784
	s_waitcnt lgkmcnt(7)
	v_mfma_f32_32x32x16_bf16 v[82:97], v[12:15], v[146:149], v[82:97]
	ds_read_b128 v[242:245], v0 offset:50816
	s_waitcnt lgkmcnt(7)
	v_mfma_f32_32x32x16_bf16 v[82:97], v[214:217], v[126:129], v[82:97]
	ds_read_b128 v[246:249], v0 offset:50848
	s_waitcnt lgkmcnt(7)
	v_mfma_f32_32x32x16_bf16 v[82:97], v[218:221], v[122:125], v[82:97]
	s_waitcnt lgkmcnt(6)
	v_mfma_f32_32x32x16_bf16 v[82:97], v[222:225], v[118:121], v[82:97]
	s_cbranch_scc0 .Lat_m2
	v_add_u32_e32 v3, v205, v208
	v_add_u32_e32 v0, 0xf000, v3
	v_add_u32_e32 v3, 0xe000, v3
	s_waitcnt lgkmcnt(5)
	v_mfma_f32_32x32x16_bf16 v[66:81], v[226:229], v[154:157], v[50:65]
	ds_read2_b64 v[226:229], v3 offset1:2
	s_waitcnt lgkmcnt(5)
	v_mfma_f32_32x32x16_bf16 v[66:81], v[230:233], v[150:153], v[66:81]
	ds_read2_b64 v[230:233], v0 offset0:32 offset1:34
	s_nop 3
	v_exp_f32_e32 v214, v82
	v_exp_f32_e32 v215, v83
	v_exp_f32_e32 v216, v84
	s_waitcnt lgkmcnt(5)
	v_mfma_f32_32x32x16_bf16 v[66:81], v[234:237], v[146:149], v[66:81]
	ds_read2_b64 v[234:237], v3 offset0:4 offset1:6
	v_exp_f32_e32 v217, v85
	v_exp_f32_e32 v218, v86
	v_exp_f32_e32 v219, v87
	s_waitcnt lgkmcnt(5)
	v_mfma_f32_32x32x16_bf16 v[66:81], v[238:241], v[126:129], v[66:81]
	ds_read2_b64 v[238:241], v0 offset0:36 offset1:38
	v_exp_f32_e32 v220, v88
	v_exp_f32_e32 v221, v89
	v_max3_f32 v159, v82, v83, v84
	v_max3_f32 v250, v85, v86, v87
	s_waitcnt lgkmcnt(5)
	v_mfma_f32_32x32x16_bf16 v[66:81], v[242:245], v[122:125], v[66:81]
	ds_read2_b64 v[242:245], v3 offset0:8 offset1:10
	v_exp_f32_e32 v222, v90
	v_exp_f32_e32 v223, v91
	v_exp_f32_e32 v224, v92
	s_waitcnt lgkmcnt(5)
	v_mfma_f32_32x32x16_bf16 v[66:81], v[246:249], v[118:121], v[66:81]
	ds_read2_b64 v[246:249], v0 offset0:40 offset1:42
	s_setprio 0
	v_exp_f32_e32 v225, v93
	v_exp_f32_e32 v12, v94
	v_exp_f32_e32 v13, v95
	v_exp_f32_e32 v14, v96
	v_exp_f32_e32 v15, v97
	v_max3_f32 v159, v159, v88, v89
	v_max3_f32 v250, v250, v90, v91
	v_max3_f32 v159, v159, v92, v93
	v_max3_f32 v250, v250, v94, v95
	v_max3_f32 v159, v159, v96, v97
	s_nop 1
	v_max3_f32 v159, v159, v66, v67
	v_max3_f32 v250, v250, v68, v69
	v_max3_f32 v159, v159, v70, v71
	v_max3_f32 v250, v250, v72, v73
	v_max3_f32 v159, v159, v74, v75
	v_max3_f32 v250, v250, v76, v77
	v_max3_f32 v159, v159, v78, v79
	v_max3_f32 v250, v250, v80, v81
	v_max_f32_e32 v0, v159, v250
	v_mov_b32_e32 v3, v0
	s_nop 1
	v_permlane32_swap_b32_e32 v0, v3
	v_max_f32_e32 v0, v0, v3
	s_nop 0
	v_cmp_lt_f32_e32 vcc, s30, v0
	s_cbranch_vccnz .Lat_r2
.Lat_c2:
	v_cvt_pk_bf16_f32 v4, v214, v215
	v_cvt_pk_bf16_f32 v5, v216, v217
	v_cvt_pk_bf16_f32 v6, v218, v219
	v_cvt_pk_bf16_f32 v7, v220, v221
	v_exp_f32_e32 v66, v66
	v_exp_f32_e32 v67, v67
	s_waitcnt lgkmcnt(4)
	v_mfma_f32_32x32x16_bf16 v[32:47], v[226:229], v[4:7], v[32:47]
	v_mfma_f32_32x32x16_bf16 v[16:31], v[230:233], v[4:7], v[16:31]
	v_cvt_pk_bf16_f32 v8, v222, v223
	v_cvt_pk_bf16_f32 v9, v224, v225
	v_cvt_pk_bf16_f32 v10, v12, v13
	v_cvt_pk_bf16_f32 v11, v14, v15
	v_exp_f32_e32 v68, v68
	v_exp_f32_e32 v69, v69
	v_exp_f32_e32 v70, v70
	v_exp_f32_e32 v71, v71
	s_waitcnt lgkmcnt(2)
	v_mfma_f32_32x32x16_bf16 v[32:47], v[234:237], v[8:11], v[32:47]
	v_mfma_f32_32x32x16_bf16 v[16:31], v[238:241], v[8:11], v[16:31]
	v_add_u32_e32 v3, v205, v208
	v_add_u32_e32 v0, 0xf000, v3
	v_add_u32_e32 v3, 0xe000, v3
	ds_read2_b64 v[226:229], v3 offset0:12 offset1:14
	ds_read2_b64 v[230:233], v0 offset0:44 offset1:46
	v_exp_f32_e32 v72, v72
	v_exp_f32_e32 v73, v73
	v_add_f32_e32 v82, v214, v66
	v_add_f32_e32 v83, v215, v67
	v_add_f32_e32 v84, v216, v68
	v_add_f32_e32 v85, v217, v69
	v_cvt_pk_bf16_f32 v4, v66, v67
	v_cvt_pk_bf16_f32 v5, v68, v69
	v_cvt_pk_bf16_f32 v6, v70, v71
	v_cvt_pk_bf16_f32 v7, v72, v73
	v_exp_f32_e32 v74, v74
	v_exp_f32_e32 v75, v75
	v_exp_f32_e32 v76, v76
	v_exp_f32_e32 v77, v77
	s_waitcnt lgkmcnt(2)
	v_mfma_f32_32x32x16_bf16 v[32:47], v[242:245], v[4:7], v[32:47]
	v_mfma_f32_32x32x16_bf16 v[16:31], v[246:249], v[4:7], v[16:31]
	v_add_f32_e32 v86, v218, v70
	v_add_f32_e32 v87, v219, v71
	v_add_f32_e32 v88, v220, v72
	v_add_f32_e32 v89, v221, v73
	v_exp_f32_e32 v78, v78
	v_exp_f32_e32 v79, v79
	v_exp_f32_e32 v80, v80
	v_exp_f32_e32 v81, v81
	v_add_f32_e32 v251, v82, v83
	v_add_f32_e32 v251, v251, v84
	v_add_f32_e32 v251, v251, v85
	v_add_f32_e32 v251, v251, v86
	v_add_f32_e32 v251, v251, v87
	v_add_f32_e32 v251, v251, v88
	v_add_f32_e32 v251, v251, v89
	v_add_f32_e32 v90, v222, v74
	v_add_f32_e32 v91, v223, v75
	v_add_f32_e32 v92, v224, v76
	v_add_f32_e32 v93, v225, v77
	v_add_f32_e32 v94, v12, v78
	v_add_f32_e32 v95, v13, v79
	v_add_f32_e32 v96, v14, v80
	v_add_f32_e32 v97, v15, v81
	v_cvt_pk_bf16_f32 v8, v74, v75
	v_cvt_pk_bf16_f32 v9, v76, v77
	v_cvt_pk_bf16_f32 v10, v78, v79
	v_cvt_pk_bf16_f32 v11, v80, v81
	s_waitcnt lgkmcnt(0)
	s_nop 1
	v_mfma_f32_32x32x16_bf16 v[32:47], v[226:229], v[8:11], v[32:47]
	v_mfma_f32_32x32x16_bf16 v[16:31], v[230:233], v[8:11], v[16:31]
	v_add_f32_e32 v251, v251, v90
	v_add_f32_e32 v251, v251, v91
	v_add_f32_e32 v251, v251, v92
	v_add_f32_e32 v251, v251, v93
	v_add_f32_e32 v251, v251, v94
	v_add_f32_e32 v251, v251, v95
	v_add_f32_e32 v251, v251, v96
	v_add_f32_e32 v251, v251, v97
	v_add_f32_e32 v48, v48, v251
	s_branch .LBB0_848

; #define LAS __attribute__((address_space(3)))
; #define MFMA32(a, b, c) __builtin_amdgcn_mfma_f32_32x32x16_bf16((a), (b), (c), 0, 0, 0)
; DI int crow(int r, int hi) { return (r & 3) + 8 * (r >> 2) + 4 * hi; }
; DI void attn_tile(bool MASK, const LAS unsigned char* Ks, const LAS unsigned char* Vs, const bf16x8 (&qr)[6], f32x16& negm, float& mrun, float& lrun, f32x16& o0, f32x16& o1,
;                                        int kv0, int qrow, int r32, int hi) {
;     ...
;         p0 = MFMA32(a0, qr[0], negm); p1 = MFMA32(a1, qr[0], negm);
;     }
; #pragma unroll
;     for (int d0 = 1; d0 < 6; ++d0) {
;         const bf16x8 a0 = *(const LAS bf16x8*)(Ks + r32 * 208 + (2 * d0 + hi) * 16);
;         const bf16x8 a1 = *(const LAS bf16x8*)(Ks + (32 + r32) * 208 + (2 * d0 + hi) * 16);
;         p0 = MFMA32(a0, qr[d0], p0); p1 = MFMA32(a1, qr[d0], p1);
;     }
;     __builtin_amdgcn_s_setprio(0);
;     if (MASK) {
;         asm volatile("" ::: "memory");
; #pragma unroll
;         for (int r = 0; r < 16; ++r) { const int kv = kv0 + crow(r, hi); if (kv > qrow) p0[r] = -INFINITY; if (kv + 32 > qrow) p1[r] = -INFINITY; }
;     }
.Lat_m2:
	s_waitcnt lgkmcnt(5)
	v_mfma_f32_32x32x16_bf16 v[66:81], v[226:229], v[154:157], v[50:65]
	s_waitcnt lgkmcnt(4)
	v_mfma_f32_32x32x16_bf16 v[66:81], v[230:233], v[150:153], v[66:81]
	s_waitcnt lgkmcnt(3)
	v_mfma_f32_32x32x16_bf16 v[66:81], v[234:237], v[146:149], v[66:81]
	s_waitcnt lgkmcnt(2)
	v_mfma_f32_32x32x16_bf16 v[66:81], v[238:241], v[126:129], v[66:81]
	s_waitcnt lgkmcnt(1)
	v_mfma_f32_32x32x16_bf16 v[66:81], v[242:245], v[122:125], v[66:81]
	s_waitcnt lgkmcnt(0)
	v_mfma_f32_32x32x16_bf16 v[66:81], v[246:249], v[118:121], v[66:81]
	s_setprio 0
	v_add_u32_e32 v3, v205, v208
	v_add_u32_e32 v0, 0xf000, v3
	v_add_u32_e32 v3, 0xe000, v3
	ds_read2_b64 v[214:217], v3 offset0:0 offset1:2
	ds_read2_b64 v[218:221], v0 offset0:32 offset1:34
	ds_read2_b64 v[222:225], v3 offset0:4 offset1:6
	ds_read2_b64 v[226:229], v0 offset0:36 offset1:38
	ds_read2_b64 v[230:233], v3 offset0:8 offset1:10
	ds_read2_b64 v[234:237], v0 offset0:40 offset1:42
	ds_read2_b64 v[238:241], v3 offset0:12 offset1:14
	ds_read2_b64 v[242:245], v0 offset0:44 offset1:46
	v_add_u32_e32 v0, s21, v207
	v_add_u32_e32 v4, 0xa0, v0
	v_add_u32_e32 v3, 0x80, v0
	v_cmp_le_i32_e32 vcc, v4, v49
	s_nop 5
	v_cndmask_b32_e32 v66, v212, v66, vcc
	v_cmp_lt_i32_e32 vcc, v3, v49
	s_nop 1
	v_cndmask_b32_e32 v83, v212, v83, vcc
	v_cmp_le_i32_e32 vcc, v3, v49
	v_add_u32_e32 v3, 0xa1, v0
	s_nop 0
	v_cndmask_b32_e32 v82, v212, v82, vcc
	v_cmp_le_i32_e32 vcc, v3, v49
	v_add_u32_e32 v3, 0x82, v0
	s_nop 0
	v_cndmask_b32_e32 v67, v212, v67, vcc
	v_cmp_le_i32_e32 vcc, v3, v49
	v_add_u32_e32 v3, 0xa2, v0
	s_nop 0
	v_cndmask_b32_e32 v84, v212, v84, vcc
	v_cmp_le_i32_e32 vcc, v3, v49
	v_add_u32_e32 v3, 0x83, v0
	s_nop 0
	v_cndmask_b32_e32 v68, v212, v68, vcc
	v_cmp_le_i32_e32 vcc, v3, v49
	v_add_u32_e32 v3, 0xa3, v0
	s_nop 0
	v_cndmask_b32_e32 v85, v212, v85, vcc
	v_cmp_le_i32_e32 vcc, v3, v49
	v_add_u32_e32 v3, 0x88, v0
	s_nop 0
	v_cndmask_b32_e32 v69, v212, v69, vcc
	v_cmp_le_i32_e32 vcc, v3, v49
	v_add_u32_e32 v3, 0xa8, v0
	s_nop 0
	v_cndmask_b32_e32 v86, v212, v86, vcc
	v_cmp_le_i32_e32 vcc, v3, v49
	v_add_u32_e32 v3, 0x89, v0
	s_nop 0
	v_cndmask_b32_e32 v70, v212, v70, vcc
	v_cmp_le_i32_e32 vcc, v3, v49
	v_add_u32_e32 v3, 0xa9, v0
	s_nop 0
	v_cndmask_b32_e32 v87, v212, v87, vcc
	v_cmp_le_i32_e32 vcc, v3, v49
	v_add_u32_e32 v3, 0x8a, v0
	s_nop 0
	v_cndmask_b32_e32 v71, v212, v71, vcc
	v_cmp_le_i32_e32 vcc, v3, v49
	v_add_u32_e32 v3, 0xaa, v0
	s_nop 0
	v_cndmask_b32_e32 v88, v212, v88, vcc
	v_cmp_le_i32_e32 vcc, v3, v49
	v_add_u32_e32 v3, 0x8b, v0
	s_nop 0
	v_cndmask_b32_e32 v72, v212, v72, vcc
	v_cmp_le_i32_e32 vcc, v3, v49
	v_add_u32_e32 v3, 0xab, v0
	s_nop 0
	v_cndmask_b32_e32 v89, v212, v89, vcc
	v_cmp_le_i32_e32 vcc, v3, v49
	v_add_u32_e32 v3, 0x90, v0
	s_nop 0
	v_cndmask_b32_e32 v73, v212, v73, vcc
	v_cmp_le_i32_e32 vcc, v3, v49
	v_add_u32_e32 v3, 0xb0, v0
	s_nop 0
	v_cndmask_b32_e32 v90, v212, v90, vcc
	v_cmp_le_i32_e32 vcc, v3, v49
	v_add_u32_e32 v3, 0x91, v0
	s_nop 0
	v_cndmask_b32_e32 v74, v212, v74, vcc
	v_cmp_le_i32_e32 vcc, v3, v49
	v_add_u32_e32 v3, 0xb1, v0
	s_nop 0
	v_cndmask_b32_e32 v91, v212, v91, vcc
	v_cmp_le_i32_e32 vcc, v3, v49
	v_add_u32_e32 v3, 0x92, v0
	s_nop 0
	v_cndmask_b32_e32 v75, v212, v75, vcc
	v_cmp_le_i32_e32 vcc, v3, v49
	v_add_u32_e32 v3, 0xb2, v0
	s_nop 0
	v_cndmask_b32_e32 v92, v212, v92, vcc
	v_cmp_le_i32_e32 vcc, v3, v49
	v_add_u32_e32 v3, 0x93, v0
	s_nop 0
	v_cndmask_b32_e32 v76, v212, v76, vcc
	v_cmp_le_i32_e32 vcc, v3, v49
	v_add_u32_e32 v3, 0xb3, v0
	s_nop 0
	v_cndmask_b32_e32 v93, v212, v93, vcc
	v_cmp_le_i32_e32 vcc, v3, v49
	v_add_u32_e32 v3, 0x98, v0
	s_nop 0
	v_cndmask_b32_e32 v77, v212, v77, vcc
	v_cmp_le_i32_e32 vcc, v3, v49
	v_add_u32_e32 v3, 0xb8, v0
	s_nop 0
	v_cndmask_b32_e32 v94, v212, v94, vcc
	v_cmp_le_i32_e32 vcc, v3, v49
	v_add_u32_e32 v3, 0x99, v0
	s_nop 0
	v_cndmask_b32_e32 v78, v212, v78, vcc
	v_cmp_le_i32_e32 vcc, v3, v49
	v_add_u32_e32 v3, 0xb9, v0
	s_nop 0
	v_cndmask_b32_e32 v95, v212, v95, vcc
	v_cmp_le_i32_e32 vcc, v3, v49
	v_add_u32_e32 v3, 0x9a, v0
	s_nop 0
	v_cndmask_b32_e32 v79, v212, v79, vcc
	v_cmp_le_i32_e32 vcc, v3, v49
	v_add_u32_e32 v3, 0xba, v0
	s_nop 0
	v_cndmask_b32_e32 v96, v212, v96, vcc
	v_cmp_le_i32_e32 vcc, v3, v49
	v_add_u32_e32 v3, 0x9b, v0
	v_add_u32_e32 v0, 0xbb, v0
	v_cndmask_b32_e32 v80, v212, v80, vcc
	v_cmp_le_i32_e32 vcc, v3, v49
	s_nop 1
	v_cndmask_b32_e32 v97, v212, v97, vcc
	v_cmp_le_i32_e32 vcc, v0, v49
	s_nop 1
	v_cndmask_b32_e32 v81, v212, v81, vcc
